# combo18 + P3: KN and selection-mask stores write-through (sc1)
# speedup vs baseline: 1.0118x; 1.0118x over previous
.LBB0_1144:
	s_waitcnt vmcnt(0)
	v_cvt_f32_f16_sdwa v21, v12 dst_sel:DWORD dst_unused:UNUSED_PAD src0_sel:WORD_1
	v_cvt_f32_f16_e32 v20, v12
	v_cvt_f32_f16_sdwa v23, v13 dst_sel:DWORD dst_unused:UNUSED_PAD src0_sel:WORD_1
	v_cvt_f32_f16_e32 v22, v13
	v_cvt_f32_f16_sdwa v13, v14 dst_sel:DWORD dst_unused:UNUSED_PAD src0_sel:WORD_1
	v_cvt_f32_f16_e32 v12, v14
	v_cvt_f32_f16_sdwa v25, v15 dst_sel:DWORD dst_unused:UNUSED_PAD src0_sel:WORD_1
	v_cvt_f32_f16_e32 v24, v15
	v_pk_mul_f32 v[14:15], v[20:21], v[20:21]
	v_pk_mul_f32 v[26:27], v[22:23], v[22:23]
	v_add_f32_e32 v14, v14, v15
	v_add_f32_e32 v14, v14, v26
	v_pk_mul_f32 v[28:29], v[12:13], v[12:13]
	v_add_f32_e32 v14, v14, v27
	v_add_f32_e32 v14, v14, v28
	v_pk_mul_f32 v[30:31], v[24:25], v[24:25]
	v_add_f32_e32 v14, v14, v29
	v_add_f32_e32 v14, v14, v30
	v_add_f32_e32 v14, v14, v31
	s_mov_b64 s[16:17], 0x21a00000
	v_mov_b32_e32 v15, 0
	v_add_f32_dpp v14, v14, v14 quad_perm:[1,0,3,2] row_mask:0xf bank_mask:0xf bound_ctrl:1
	v_lshl_add_u64 v[18:19], v[18:19], 0, s[16:17]
	v_mov_b32_e32 v26, 0
	v_add_f32_dpp v14, v14, v14 quad_perm:[2,3,0,1] row_mask:0xf bank_mask:0xf bound_ctrl:1
	s_andn2_b64 vcc, exec, s[0:1]
	s_nop 0
	v_add_f32_dpp v14, v14, v14 row_half_mirror row_mask:0xf bank_mask:0xf bound_ctrl:1
	s_nop 1
	v_mov_b32_dpp v15, v14 row_mirror row_mask:0xf bank_mask:0xf
	s_cbranch_vccnz .LBB0_1146
	v_add_f32_e32 v14, v14, v15
	v_mov_b32_e32 v15, 0x358637bd
	v_fmac_f32_e32 v15, 0x3c000000, v14
	s_mov_b32 s0, 0xf800000
	v_mul_f32_e32 v14, 0x4f800000, v15
	v_cmp_gt_f32_e32 vcc, s0, v15
	s_ashr_i32 s89, s88, 31
	s_nop 0
	v_cndmask_b32_e32 v14, v15, v14, vcc
	v_sqrt_f32_e32 v15, v14
	s_nop 0
	v_add_u32_e32 v27, -1, v15
	v_fma_f32 v28, -v27, v15, v14
	v_cmp_ge_f32_e64 s[0:1], 0, v28
	v_add_u32_e32 v28, 1, v15
	s_nop 0
	v_cndmask_b32_e64 v27, v15, v27, s[0:1]
	v_fma_f32 v15, -v28, v15, v14
	v_cmp_lt_f32_e64 s[0:1], 0, v15
	s_nop 1
	v_cndmask_b32_e64 v15, v27, v28, s[0:1]
	v_mul_f32_e32 v27, 0x37800000, v15
	v_cndmask_b32_e32 v15, v15, v27, vcc
	v_mov_b32_e32 v27, 0x260
	v_cmp_class_f32_e32 vcc, v14, v27
	s_nop 1
	v_cndmask_b32_e32 v27, v15, v14, vcc
	v_div_scale_f32 v28, s[0:1], v27, v27, 1.0
	v_rcp_f32_e32 v29, v28
	s_lshl_b64 s[0:1], s[88:89], 10
	v_lshl_add_u64 v[14:15], v[18:19], 0, s[0:1]
	v_fma_f32 v30, -v28, v29, 1.0
	v_fmac_f32_e32 v29, v30, v29
	v_div_scale_f32 v30, vcc, 1.0, v27, 1.0
	v_mul_f32_e32 v31, v30, v29
	v_fma_f32 v32, -v28, v31, v30
	v_fmac_f32_e32 v31, v32, v29
	v_fma_f32 v28, -v28, v31, v30
	v_div_fmas_f32 v28, v28, v29, v31
	v_div_fixup_f32 v28, v28, v27, 1.0
	v_pk_mul_f32 v[20:21], v[28:29], v[20:21] op_sel_hi:[0,1]
	v_pk_mul_f32 v[22:23], v[28:29], v[22:23] op_sel_hi:[0,1]
	v_pk_mul_f32 v[12:13], v[28:29], v[12:13] op_sel_hi:[0,1]
	v_cvt_pk_f16_f32 v20, v20, v21
	v_cvt_pk_f16_f32 v21, v22, v23
	v_cvt_pk_f16_f32 v22, v12, v13
	v_pk_mul_f32 v[12:13], v[28:29], v[24:25] op_sel_hi:[0,1]
	v_cvt_pk_f16_f32 v23, v12, v13
	global_store_dwordx4 v[14:15], v[20:23], off sc1
.LBB0_1146:
	v_cvt_f32_f16_sdwa v13, v8 dst_sel:DWORD dst_unused:UNUSED_PAD src0_sel:WORD_1
	v_cvt_f32_f16_e32 v12, v8
	v_cvt_f32_f16_sdwa v15, v9 dst_sel:DWORD dst_unused:UNUSED_PAD src0_sel:WORD_1
	v_cvt_f32_f16_e32 v14, v9
	v_cvt_f32_f16_sdwa v9, v10 dst_sel:DWORD dst_unused:UNUSED_PAD src0_sel:WORD_1
	v_cvt_f32_f16_e32 v8, v10
	v_cvt_f32_f16_sdwa v21, v11 dst_sel:DWORD dst_unused:UNUSED_PAD src0_sel:WORD_1
	v_cvt_f32_f16_e32 v20, v11
	v_pk_mul_f32 v[10:11], v[12:13], v[12:13]
	v_pk_mul_f32 v[22:23], v[14:15], v[14:15]
	v_add_f32_e32 v10, v10, v11
	v_add_f32_e32 v10, v10, v22
	v_pk_mul_f32 v[24:25], v[8:9], v[8:9]
	v_add_f32_e32 v10, v10, v23
	v_add_f32_e32 v10, v10, v24
	v_pk_mul_f32 v[28:29], v[20:21], v[20:21]
	v_add_f32_e32 v10, v10, v25
	v_add_f32_e32 v10, v10, v28
	v_add_f32_e32 v10, v10, v29
	s_andn2_b64 vcc, exec, s[14:15]
	s_nop 0
	v_add_f32_dpp v10, v10, v10 quad_perm:[1,0,3,2] row_mask:0xf bank_mask:0xf bound_ctrl:1
	s_nop 1
	v_add_f32_dpp v10, v10, v10 quad_perm:[2,3,0,1] row_mask:0xf bank_mask:0xf bound_ctrl:1
	s_nop 1
	v_add_f32_dpp v10, v10, v10 row_half_mirror row_mask:0xf bank_mask:0xf bound_ctrl:1
	s_nop 1
	v_mov_b32_dpp v26, v10 row_mirror row_mask:0xf bank_mask:0xf
	s_cbranch_vccnz .LBB0_1148
	v_add_f32_e32 v10, v10, v26
	v_mov_b32_e32 v11, 0x358637bd
	v_fmac_f32_e32 v11, 0x3c000000, v10
	s_mov_b32 s0, 0xf800000
	v_mul_f32_e32 v10, 0x4f800000, v11
	v_cmp_gt_f32_e32 vcc, s0, v11
	s_ashr_i32 s13, s12, 31
	s_nop 0
	v_cndmask_b32_e32 v10, v11, v10, vcc
	v_sqrt_f32_e32 v11, v10
	s_nop 0
	v_add_u32_e32 v22, -1, v11
	v_fma_f32 v23, -v22, v11, v10
	v_cmp_ge_f32_e64 s[0:1], 0, v23
	v_add_u32_e32 v23, 1, v11
	s_nop 0
	v_cndmask_b32_e64 v22, v11, v22, s[0:1]
	v_fma_f32 v11, -v23, v11, v10
	v_cmp_lt_f32_e64 s[0:1], 0, v11
	s_nop 1
	v_cndmask_b32_e64 v11, v22, v23, s[0:1]
	v_mul_f32_e32 v22, 0x37800000, v11
	v_cndmask_b32_e32 v11, v11, v22, vcc
	v_mov_b32_e32 v22, 0x260
	v_cmp_class_f32_e32 vcc, v10, v22
	s_nop 1
	v_cndmask_b32_e32 v10, v11, v10, vcc
	v_div_scale_f32 v11, s[0:1], v10, v10, 1.0
	v_rcp_f32_e32 v24, v11
	s_lshl_b64 s[0:1], s[12:13], 10
	v_lshl_add_u64 v[22:23], v[18:19], 0, s[0:1]
	v_fma_f32 v25, -v11, v24, 1.0
	v_fmac_f32_e32 v24, v25, v24
	v_div_scale_f32 v25, vcc, 1.0, v10, 1.0
	v_mul_f32_e32 v26, v25, v24
	v_fma_f32 v27, -v11, v26, v25
	v_fmac_f32_e32 v26, v27, v24
	v_fma_f32 v11, -v11, v26, v25
	v_div_fmas_f32 v11, v11, v24, v26
	v_div_fixup_f32 v24, v11, v10, 1.0
	v_pk_mul_f32 v[10:11], v[24:25], v[12:13] op_sel_hi:[0,1]
	v_pk_mul_f32 v[12:13], v[24:25], v[14:15] op_sel_hi:[0,1]
	v_pk_mul_f32 v[8:9], v[24:25], v[8:9] op_sel_hi:[0,1]
	v_cvt_pk_f16_f32 v10, v10, v11
	v_cvt_pk_f16_f32 v11, v12, v13
	v_cvt_pk_f16_f32 v12, v8, v9
	v_pk_mul_f32 v[8:9], v[24:25], v[20:21] op_sel_hi:[0,1]
	v_cvt_pk_f16_f32 v13, v8, v9
	global_store_dwordx4 v[22:23], v[10:13], off sc1
.LBB0_1148:
	v_cvt_f32_f16_sdwa v9, v4 dst_sel:DWORD dst_unused:UNUSED_PAD src0_sel:WORD_1
	v_cvt_f32_f16_e32 v8, v4
	v_cvt_f32_f16_sdwa v11, v5 dst_sel:DWORD dst_unused:UNUSED_PAD src0_sel:WORD_1
	v_cvt_f32_f16_e32 v10, v5
	v_cvt_f32_f16_sdwa v5, v6 dst_sel:DWORD dst_unused:UNUSED_PAD src0_sel:WORD_1
	v_cvt_f32_f16_e32 v4, v6
	v_cvt_f32_f16_sdwa v13, v7 dst_sel:DWORD dst_unused:UNUSED_PAD src0_sel:WORD_1
	v_cvt_f32_f16_e32 v12, v7
	v_pk_mul_f32 v[6:7], v[8:9], v[8:9]
	v_pk_mul_f32 v[14:15], v[10:11], v[10:11]
	v_add_f32_e32 v6, v6, v7
	v_add_f32_e32 v6, v6, v14
	v_pk_mul_f32 v[20:21], v[4:5], v[4:5]
	v_add_f32_e32 v6, v6, v15
	v_add_f32_e32 v6, v6, v20
	v_pk_mul_f32 v[22:23], v[12:13], v[12:13]
	v_add_f32_e32 v6, v6, v21
	v_add_f32_e32 v6, v6, v22
	v_add_f32_e32 v6, v6, v23
	v_mov_b32_e32 v7, 0
	v_mov_b32_e32 v14, 0
	v_add_f32_dpp v6, v6, v6 quad_perm:[1,0,3,2] row_mask:0xf bank_mask:0xf bound_ctrl:1
	s_andn2_b64 vcc, exec, s[10:11]
	s_nop 0
	v_add_f32_dpp v6, v6, v6 quad_perm:[2,3,0,1] row_mask:0xf bank_mask:0xf bound_ctrl:1
	s_nop 1
	v_add_f32_dpp v6, v6, v6 row_half_mirror row_mask:0xf bank_mask:0xf bound_ctrl:1
	s_nop 1
	v_mov_b32_dpp v7, v6 row_mirror row_mask:0xf bank_mask:0xf
	s_cbranch_vccnz .LBB0_1150
	v_add_f32_e32 v6, v6, v7
	v_mov_b32_e32 v7, 0x358637bd
	v_fmac_f32_e32 v7, 0x3c000000, v6
	s_mov_b32 s0, 0xf800000
	v_mul_f32_e32 v6, 0x4f800000, v7
	v_cmp_gt_f32_e32 vcc, s0, v7
	s_ashr_i32 s9, s8, 31
	s_nop 0
	v_cndmask_b32_e32 v6, v7, v6, vcc
	v_sqrt_f32_e32 v7, v6
	s_nop 0
	v_add_u32_e32 v15, -1, v7
	v_fma_f32 v20, -v15, v7, v6
	v_cmp_ge_f32_e64 s[0:1], 0, v20
	v_add_u32_e32 v20, 1, v7
	s_nop 0
	v_cndmask_b32_e64 v15, v7, v15, s[0:1]
	v_fma_f32 v7, -v20, v7, v6
	v_cmp_lt_f32_e64 s[0:1], 0, v7
	s_nop 1
	v_cndmask_b32_e64 v7, v15, v20, s[0:1]
	v_mul_f32_e32 v15, 0x37800000, v7
	v_cndmask_b32_e32 v7, v7, v15, vcc
	v_mov_b32_e32 v15, 0x260
	v_cmp_class_f32_e32 vcc, v6, v15
	s_nop 1
	v_cndmask_b32_e32 v6, v7, v6, vcc
	v_div_scale_f32 v7, s[0:1], v6, v6, 1.0
	v_rcp_f32_e32 v15, v7
	s_lshl_b64 s[0:1], s[8:9], 10
	v_lshl_add_u64 v[20:21], v[18:19], 0, s[0:1]
	v_fma_f32 v22, -v7, v15, 1.0
	v_fmac_f32_e32 v15, v22, v15
	v_div_scale_f32 v22, vcc, 1.0, v6, 1.0
	v_mul_f32_e32 v23, v22, v15
	v_fma_f32 v24, -v7, v23, v22
	v_fmac_f32_e32 v23, v24, v15
	v_fma_f32 v7, -v7, v23, v22
	v_div_fmas_f32 v7, v7, v15, v23
	v_div_fixup_f32 v22, v7, v6, 1.0
	v_pk_mul_f32 v[6:7], v[22:23], v[8:9] op_sel_hi:[0,1]
	v_pk_mul_f32 v[8:9], v[22:23], v[10:11] op_sel_hi:[0,1]
	v_pk_mul_f32 v[4:5], v[22:23], v[4:5] op_sel_hi:[0,1]
	v_cvt_pk_f16_f32 v6, v6, v7
	v_cvt_pk_f16_f32 v7, v8, v9
	v_cvt_pk_f16_f32 v8, v4, v5
	v_pk_mul_f32 v[4:5], v[22:23], v[12:13] op_sel_hi:[0,1]
	v_cvt_pk_f16_f32 v9, v4, v5
	global_store_dwordx4 v[20:21], v[6:9], off sc1
.LBB0_1150:
	v_cvt_f32_f16_sdwa v5, v0 dst_sel:DWORD dst_unused:UNUSED_PAD src0_sel:WORD_1
	v_cvt_f32_f16_e32 v4, v0
	v_cvt_f32_f16_sdwa v7, v1 dst_sel:DWORD dst_unused:UNUSED_PAD src0_sel:WORD_1
	v_cvt_f32_f16_e32 v6, v1
	v_cvt_f32_f16_sdwa v1, v2 dst_sel:DWORD dst_unused:UNUSED_PAD src0_sel:WORD_1
	v_cvt_f32_f16_e32 v0, v2
	v_cvt_f32_f16_sdwa v9, v3 dst_sel:DWORD dst_unused:UNUSED_PAD src0_sel:WORD_1
	v_cvt_f32_f16_e32 v8, v3
	v_pk_mul_f32 v[2:3], v[4:5], v[4:5]
	v_pk_mul_f32 v[10:11], v[6:7], v[6:7]
	v_add_f32_e32 v2, v2, v3
	v_add_f32_e32 v2, v2, v10
	v_pk_mul_f32 v[12:13], v[0:1], v[0:1]
	v_add_f32_e32 v2, v2, v11
	v_add_f32_e32 v2, v2, v12
	v_pk_mul_f32 v[20:21], v[8:9], v[8:9]
	v_add_f32_e32 v2, v2, v13
	v_add_f32_e32 v2, v2, v20
	v_add_f32_e32 v2, v2, v21
	s_andn2_b64 vcc, exec, s[6:7]
	s_nop 0
	v_add_f32_dpp v2, v2, v2 quad_perm:[1,0,3,2] row_mask:0xf bank_mask:0xf bound_ctrl:1
	s_nop 1
	v_add_f32_dpp v2, v2, v2 quad_perm:[2,3,0,1] row_mask:0xf bank_mask:0xf bound_ctrl:1
	s_nop 1
	v_add_f32_dpp v2, v2, v2 row_half_mirror row_mask:0xf bank_mask:0xf bound_ctrl:1
	s_nop 1
	v_mov_b32_dpp v14, v2 row_mirror row_mask:0xf bank_mask:0xf
	s_cbranch_vccnz .LBB0_1152
	v_add_f32_e32 v2, v2, v14
	v_mov_b32_e32 v3, 0x358637bd
	v_fmac_f32_e32 v3, 0x3c000000, v2
	s_mov_b32 s0, 0xf800000
	v_mul_f32_e32 v2, 0x4f800000, v3
	v_cmp_gt_f32_e32 vcc, s0, v3
	s_ashr_i32 s5, s4, 31
	s_nop 0
	v_cndmask_b32_e32 v2, v3, v2, vcc
	v_sqrt_f32_e32 v3, v2
	s_nop 0
	v_add_u32_e32 v10, -1, v3
	v_fma_f32 v11, -v10, v3, v2
	v_cmp_ge_f32_e64 s[0:1], 0, v11
	v_add_u32_e32 v11, 1, v3
	s_nop 0
	v_cndmask_b32_e64 v10, v3, v10, s[0:1]
	v_fma_f32 v3, -v11, v3, v2
	v_cmp_lt_f32_e64 s[0:1], 0, v3
	s_nop 1
	v_cndmask_b32_e64 v3, v10, v11, s[0:1]
	v_mul_f32_e32 v10, 0x37800000, v3
	v_cndmask_b32_e32 v3, v3, v10, vcc
	v_mov_b32_e32 v10, 0x260
	v_cmp_class_f32_e32 vcc, v2, v10
	s_nop 1
	v_cndmask_b32_e32 v2, v3, v2, vcc
	v_div_scale_f32 v3, s[0:1], v2, v2, 1.0
	v_rcp_f32_e32 v12, v3
	s_lshl_b64 s[0:1], s[4:5], 10
	v_lshl_add_u64 v[10:11], v[18:19], 0, s[0:1]
	v_fma_f32 v13, -v3, v12, 1.0
	v_fmac_f32_e32 v12, v13, v12
	v_div_scale_f32 v13, vcc, 1.0, v2, 1.0
	v_mul_f32_e32 v14, v13, v12
	v_fma_f32 v15, -v3, v14, v13
	v_fmac_f32_e32 v14, v15, v12
	v_fma_f32 v3, -v3, v14, v13
	v_div_fmas_f32 v3, v3, v12, v14
	v_div_fixup_f32 v12, v3, v2, 1.0
	v_pk_mul_f32 v[2:3], v[12:13], v[4:5] op_sel_hi:[0,1]
	v_pk_mul_f32 v[4:5], v[12:13], v[6:7] op_sel_hi:[0,1]
	v_pk_mul_f32 v[0:1], v[12:13], v[0:1] op_sel_hi:[0,1]
	v_cvt_pk_f16_f32 v2, v2, v3
	v_cvt_pk_f16_f32 v3, v4, v5
	v_cvt_pk_f16_f32 v4, v0, v1
	v_pk_mul_f32 v[0:1], v[12:13], v[8:9] op_sel_hi:[0,1]
	v_cvt_pk_f16_f32 v5, v0, v1
	global_store_dwordx4 v[10:11], v[2:5], off sc1

.LBB0_1154:
	v_add_co_u32_e32 v4, vcc, 0xf4100000, v0
	s_add_i32 s4, s4, s76
	s_nop 0
	v_addc_co_u32_e32 v5, vcc, -1, v1, vcc
	global_load_dwordx4 v[4:7], v[4:5], off
	s_cmpk_gt_i32 s4, 0x1fff
	s_waitcnt vmcnt(0)
	v_cvt_f32_f16_e32 v12, v4
	v_cvt_f32_f16_sdwa v13, v4 dst_sel:DWORD dst_unused:UNUSED_PAD src0_sel:WORD_1
	v_cvt_f32_f16_e32 v8, v7
	v_cvt_f32_f16_sdwa v9, v7 dst_sel:DWORD dst_unused:UNUSED_PAD src0_sel:WORD_1
	v_cvt_f32_f16_e32 v10, v6
	v_cvt_f32_f16_sdwa v11, v6 dst_sel:DWORD dst_unused:UNUSED_PAD src0_sel:WORD_1
	v_cvt_f32_f16_e32 v6, v5
	v_cvt_f32_f16_sdwa v7, v5 dst_sel:DWORD dst_unused:UNUSED_PAD src0_sel:WORD_1
	v_pk_mul_f32 v[18:19], v[12:13], v[12:13]
	v_pk_mul_f32 v[14:15], v[10:11], v[10:11]
	v_add_f32_e32 v18, v18, v19
	v_pk_mul_f32 v[16:17], v[6:7], v[6:7]
	v_pk_mul_f32 v[4:5], v[8:9], v[8:9]
	v_add_f32_e32 v16, v18, v16
	v_add_f32_e32 v16, v16, v17
	v_add_f32_e32 v14, v16, v14
	v_add_f32_e32 v14, v14, v15
	v_add_f32_e32 v4, v14, v4
	v_add_f32_e32 v4, v4, v5
	s_nop 1
	v_add_f32_dpp v4, v4, v4 quad_perm:[1,0,3,2] row_mask:0xf bank_mask:0xf bound_ctrl:1
	s_nop 1
	v_add_f32_dpp v4, v4, v4 quad_perm:[2,3,0,1] row_mask:0xf bank_mask:0xf bound_ctrl:1
	s_nop 1
	v_add_f32_dpp v4, v4, v4 row_half_mirror row_mask:0xf bank_mask:0xf bound_ctrl:1
	s_nop 1
	v_add_f32_dpp v4, v4, v4 row_mirror row_mask:0xf bank_mask:0xf bound_ctrl:1
	v_fmamk_f32 v4, v4, 0x3c000000, v2
	v_mul_f32_e32 v5, 0x4f800000, v4
	v_cmp_gt_f32_e32 vcc, s3, v4
	s_nop 1
	v_cndmask_b32_e32 v4, v4, v5, vcc
	v_sqrt_f32_e32 v5, v4
	s_nop 0
	v_add_u32_e32 v14, -1, v5
	v_add_u32_e32 v15, 1, v5
	v_fma_f32 v16, -v14, v5, v4
	v_fma_f32 v17, -v15, v5, v4
	v_cmp_ge_f32_e64 s[0:1], 0, v16
	s_nop 1
	v_cndmask_b32_e64 v5, v5, v14, s[0:1]
	v_cmp_lt_f32_e64 s[0:1], 0, v17
	s_nop 1
	v_cndmask_b32_e64 v5, v5, v15, s[0:1]
	v_mul_f32_e32 v14, 0x37800000, v5
	v_cndmask_b32_e32 v5, v5, v14, vcc
	v_cmp_class_f32_e32 vcc, v4, v3
	s_nop 1
	v_cndmask_b32_e32 v4, v5, v4, vcc
	v_div_scale_f32 v5, s[0:1], v4, v4, 1.0
	v_rcp_f32_e32 v14, v5
	v_div_scale_f32 v15, vcc, 1.0, v4, 1.0
	v_fma_f32 v16, -v5, v14, 1.0
	v_fmac_f32_e32 v14, v16, v14
	v_mul_f32_e32 v16, v15, v14
	v_fma_f32 v17, -v5, v16, v15
	v_fmac_f32_e32 v16, v17, v14
	v_fma_f32 v5, -v5, v16, v15
	v_div_fmas_f32 v5, v5, v14, v16
	v_div_fixup_f32 v4, v5, v4, 1.0
	v_pk_mul_f32 v[12:13], v[4:5], v[12:13] op_sel_hi:[0,1]
	v_pk_mul_f32 v[6:7], v[4:5], v[6:7] op_sel_hi:[0,1]
	v_pk_mul_f32 v[10:11], v[4:5], v[10:11] op_sel_hi:[0,1]
	v_pk_mul_f32 v[8:9], v[4:5], v[8:9] op_sel_hi:[0,1]
	v_cvt_pk_f16_f32 v4, v12, v13
	v_cvt_pk_f16_f32 v5, v6, v7
	v_cvt_pk_f16_f32 v6, v10, v11
	v_cvt_pk_f16_f32 v7, v8, v9
	global_store_dwordx4 v[0:1], v[4:7], off sc1
	v_lshl_add_u64 v[0:1], v[0:1], 0, s[6:7]
	s_cbranch_scc0 .LBB0_1154

.LBB0_1195:
	s_waitcnt lgkmcnt(0)
	v_lshlrev_b32_e32 v98, 1, v128
	v_ashrrev_i32_e32 v99, 31, v98
	v_lshl_add_u64 v[98:99], v[98:99], 2, s[16:17]
	global_store_dwordx2 v[98:99], v[96:97], off sc1
	s_or_b64 exec, exec, s[4:5]
	s_andn2_b64 vcc, exec, s[6:7]
	s_cbranch_vccz .LBB0_1343

.LBB0_1499:
	s_and_saveexec_b64 s[4:5], s[0:1]
	s_cbranch_execz .LBB0_1157
	v_lshlrev_b32_e32 v0, 1, v128
	v_ashrrev_i32_e32 v1, 31, v0
	v_lshl_add_u64 v[0:1], v[0:1], 2, s[16:17]
	s_waitcnt lgkmcnt(0)
	global_store_dwordx2 v[0:1], v[96:97], off offset:256 sc1
	s_branch .LBB0_1157
